# GEMM engine: dropped the LDS-read wait in front of the pre-MFMA barrier (the wait after the barrier covers it)
# speedup vs baseline: 1.0075x; 1.0075x over previous
; #define PG8_STAGE(bufoff, gbase, voff) do { _Pragma("unroll") for (int _i = 0; _i < 2; ++_i) \
;         __builtin_amdgcn_global_load_lds((const unsigned*)((const char*)(gbase) + (voff)[_i]), (LAS unsigned*)(lds + (bufoff) + ldsw + _i * 8192), 16, 0, 0); } while (0)
; #define PG8_LDA(dst, b, h) do { _Pragma("unroll") for (int m = 0; m < 4; ++m) _Pragma("unroll") for (int k = 0; k < 2; ++k) dst[m][k] = *(const LAS bf16x8*)(lds + PG8_SA(b, h) + aoff + m * 2048 + k * 1024); } while (0)
; #define PG8_LDB(dst, b, h) do { _Pragma("unroll") for (int n = 0; n < 2; ++n) _Pragma("unroll") for (int k = 0; k < 2; ++k) dst[n][k] = *(const LAS bf16x8*)(lds + PG8_SB(b, h) + boff + n * 2048 + k * 1024); } while (0)
; #define PG8_WAIT_V(n) asm volatile("s_waitcnt vmcnt(" #n ")" ::: "memory")
; #define PG8_WAIT_L(n) asm volatile("s_waitcnt lgkmcnt(" #n ")" ::: "memory")
; __device__ __forceinline__ void gemm_phase(LAS unsigned char* lds, const Desc& g, int G, int cidx, int tid) {
;     ...
;         for (int t = 0; t < nt; t += 2) {
;             const bool last = (t == nt - 2);
;             const char* a1 = cA + (size_t)(t + 1) * kstep;
;             const char* a2 = last ? nA : cA + (size_t)(t + 2) * kstep; const char* b2 = last ? nB : cB + (size_t)(t + 2) * kstep;
;             const char* a3 = a2 + kstep; const char* b3 = b2 + kstep;
;             PG8_LDB(B0, 0, 0); PG8_LDB(B1, 0, 1); PG8_SCHED; PG8_LDA(At, 0, 0); PG8_STAGE(PG8_SA(1, 1), a1 + hstepA, voffA);
;             PG8_WAIT_V(8); PG8_WAIT_L(0); PG8_BAR; PG8_MMA(0, 0, At, B0); PG8_MMA(0, 1, At, B1); PG8_BAR; PG8_SCHED;
;             PG8_LDA(At, 0, 1); PG8_STAGE(PG8_SB(0, 0), b2, voffB); PG8_STAGE(PG8_SB(0, 1), b2 + hstepB, voffB); PG8_STAGE(PG8_SA(0, 0), a2, voffA);
;             PG8_WAIT_V(8); PG8_WAIT_L(0); PG8_BAR; PG8_MMA(1, 0, At, B0); PG8_MMA(1, 1, At, B1); PG8_BAR; PG8_SCHED;
;             PG8_LDB(B0, 1, 0); PG8_LDB(B1, 1, 1); PG8_SCHED; PG8_LDA(At, 1, 0); PG8_STAGE(PG8_SA(0, 1), a2 + hstepA, voffA);
;             PG8_WAIT_V(8); PG8_WAIT_L(0); PG8_BAR; PG8_MMA(0, 0, At, B0); PG8_MMA(0, 1, At, B1); PG8_BAR; PG8_SCHED;
;             PG8_LDA(At, 1, 1); PG8_STAGE(PG8_SB(1, 0), b3, voffB); PG8_STAGE(PG8_SB(1, 1), b3 + hstepB, voffB); PG8_STAGE(PG8_SA(1, 0), a3, voffA);
;             PG8_WAIT_V(8); PG8_WAIT_L(0); PG8_BAR; PG8_MMA(1, 0, At, B0); PG8_MMA(1, 1, At, B1); PG8_BAR; PG8_SCHED;
;         }
.LBB0_199:
	s_add_u32 s52, s50, 0x100
	s_addc_u32 s53, s51, 0
	s_add_i32 s42, 0, 0x10000
	s_cmp_eq_u32 s63, 62
	s_cselect_b32 s59, s1, s53
	s_cselect_b32 s58, s0, s52
	v_add_u32_e32 v142, s42, v139
	s_cselect_b32 s57, s49, s62
	s_cselect_b32 s56, s48, s61
	s_add_i32 s43, 0, 0x14000
	ds_read_b128 v[156:159], v142
	ds_read_b128 v[160:163], v142 offset:1024
	ds_read_b128 v[164:167], v142 offset:2048
	ds_read_b128 v[168:171], v142 offset:3072
	v_add_u32_e32 v142, s43, v139
	ds_read_b128 v[172:175], v142
	ds_read_b128 v[176:179], v142 offset:1024
	ds_read_b128 v[180:183], v142 offset:2048
	ds_read_b128 v[184:187], v142 offset:3072
	v_lshl_add_u64 v[142:143], s[50:51], 0, v[136:137]
	s_add_i32 m0, s7, 0xc000
	ds_read_b128 v[188:191], v141
	ds_read_b128 v[192:195], v141 offset:1024
	ds_read_b128 v[196:199], v141 offset:2048
	ds_read_b128 v[206:209], v141 offset:3072
	ds_read_b128 v[210:213], v141 offset:4096
	ds_read_b128 v[214:217], v141 offset:5120
	ds_read_b128 v[218:221], v141 offset:6144
	ds_read_b128 v[222:225], v141 offset:7168
	global_load_lds_dwordx4 v[142:143], off
	v_lshl_add_u64 v[142:143], s[50:51], 0, v[134:135]
	s_add_i32 m0, s7, 0xe000
	s_nop 0
	global_load_lds_dwordx4 v[142:143], off
	s_waitcnt vmcnt(8)
	s_barrier
	s_setprio 1
	s_waitcnt lgkmcnt(0)
	v_mfma_f32_16x16x32_bf16 v[124:127], v[156:159], v[188:191], v[124:127]
	v_mfma_f32_16x16x32_bf16 v[120:123], v[164:167], v[188:191], v[120:123]
	v_mfma_f32_16x16x32_bf16 v[108:111], v[156:159], v[196:199], v[108:111]
	v_mfma_f32_16x16x32_bf16 v[104:107], v[164:167], v[196:199], v[104:107]
	v_mfma_f32_16x16x32_bf16 v[92:95], v[156:159], v[210:213], v[92:95]
	v_mfma_f32_16x16x32_bf16 v[88:91], v[164:167], v[210:213], v[88:91]
	v_mfma_f32_16x16x32_bf16 v[76:79], v[156:159], v[218:221], v[76:79]
	v_mfma_f32_16x16x32_bf16 v[72:75], v[164:167], v[218:221], v[72:75]
	v_mfma_f32_16x16x32_bf16 v[124:127], v[160:163], v[192:195], v[124:127]
	v_mfma_f32_16x16x32_bf16 v[120:123], v[168:171], v[192:195], v[120:123]
	v_mfma_f32_16x16x32_bf16 v[108:111], v[160:163], v[206:209], v[108:111]
	v_mfma_f32_16x16x32_bf16 v[104:107], v[168:171], v[206:209], v[104:107]
	v_mfma_f32_16x16x32_bf16 v[92:95], v[160:163], v[214:217], v[92:95]
	v_mfma_f32_16x16x32_bf16 v[88:91], v[168:171], v[214:217], v[88:91]
	v_mfma_f32_16x16x32_bf16 v[76:79], v[160:163], v[222:225], v[76:79]
	v_mfma_f32_16x16x32_bf16 v[72:75], v[168:171], v[222:225], v[72:75]
	s_setprio 0
	s_setprio 1
	v_mfma_f32_16x16x32_bf16 v[116:119], v[172:175], v[188:191], v[116:119]
	v_mfma_f32_16x16x32_bf16 v[112:115], v[180:183], v[188:191], v[112:115]
	v_mfma_f32_16x16x32_bf16 v[100:103], v[172:175], v[196:199], v[100:103]
	v_mfma_f32_16x16x32_bf16 v[96:99], v[180:183], v[196:199], v[96:99]
	v_mfma_f32_16x16x32_bf16 v[84:87], v[172:175], v[210:213], v[84:87]
	v_mfma_f32_16x16x32_bf16 v[80:83], v[180:183], v[210:213], v[80:83]
	v_mfma_f32_16x16x32_bf16 v[68:71], v[172:175], v[218:221], v[68:71]
	v_mfma_f32_16x16x32_bf16 v[64:67], v[180:183], v[218:221], v[64:67]
	v_mfma_f32_16x16x32_bf16 v[116:119], v[176:179], v[192:195], v[116:119]
	v_mfma_f32_16x16x32_bf16 v[112:115], v[184:187], v[192:195], v[112:115]
	v_mfma_f32_16x16x32_bf16 v[100:103], v[176:179], v[206:209], v[100:103]
	v_mfma_f32_16x16x32_bf16 v[96:99], v[184:187], v[206:209], v[96:99]
	v_mfma_f32_16x16x32_bf16 v[84:87], v[176:179], v[214:217], v[84:87]
	v_mfma_f32_16x16x32_bf16 v[80:83], v[184:187], v[214:217], v[80:83]
	v_mfma_f32_16x16x32_bf16 v[68:71], v[176:179], v[222:225], v[68:71]
	v_mfma_f32_16x16x32_bf16 v[64:67], v[184:187], v[222:225], v[64:67]
	s_setprio 0
	s_barrier
	s_add_i32 s42, s42, s6
	v_lshl_add_u64 v[142:143], s[56:57], 0, v[144:145]
	s_mov_b32 m0, s42
	ds_read_b128 v[188:191], v141 offset:16384
	ds_read_b128 v[192:195], v141 offset:17408
	ds_read_b128 v[196:199], v141 offset:18432
	ds_read_b128 v[206:209], v141 offset:19456
	ds_read_b128 v[210:213], v141 offset:20480
	ds_read_b128 v[214:217], v141 offset:21504
	ds_read_b128 v[218:221], v141 offset:22528
	ds_read_b128 v[222:225], v141 offset:23552
	global_load_lds_dwordx4 v[142:143], off
	s_add_i32 m0, s42, 0x2000
	s_add_u32 s50, s56, 0x110000
	v_lshl_add_u64 v[146:147], s[56:57], 0, v[128:129]
	s_addc_u32 s51, s57, 0
	s_add_i32 s42, s43, s6
	global_load_lds_dwordx4 v[146:147], off
	v_lshl_add_u64 v[148:149], s[50:51], 0, v[144:145]
	s_mov_b32 m0, s42
	v_lshl_add_u64 v[200:201], s[58:59], 0, v[130:131]
	global_load_lds_dwordx4 v[148:149], off
	v_lshl_add_u64 v[148:149], s[50:51], 0, v[128:129]
	s_add_i32 m0, s42, 0x2000
	s_nop 0
	global_load_lds_dwordx4 v[148:149], off
	v_lshl_add_u64 v[148:149], s[58:59], 0, v[132:133]
	s_mov_b32 m0, s7
	s_nop 0
	global_load_lds_dwordx4 v[148:149], off
	s_mov_b32 m0, s13
	s_nop 0
	global_load_lds_dwordx4 v[200:201], off
	s_waitcnt vmcnt(8)
	s_barrier
; #define PG8_STAGE(bufoff, gbase, voff) do { _Pragma("unroll") for (int _i = 0; _i < 2; ++_i) \
;         __builtin_amdgcn_global_load_lds((const unsigned*)((const char*)(gbase) + (voff)[_i]), (LAS unsigned*)(lds + (bufoff) + ldsw + _i * 8192), 16, 0, 0); } while (0)
; #define PG8_LDA(dst, b, h) do { _Pragma("unroll") for (int m = 0; m < 4; ++m) _Pragma("unroll") for (int k = 0; k < 2; ++k) dst[m][k] = *(const LAS bf16x8*)(lds + PG8_SA(b, h) + aoff + m * 2048 + k * 1024); } while (0)
; #define PG8_LDB(dst, b, h) do { _Pragma("unroll") for (int n = 0; n < 2; ++n) _Pragma("unroll") for (int k = 0; k < 2; ++k) dst[n][k] = *(const LAS bf16x8*)(lds + PG8_SB(b, h) + boff + n * 2048 + k * 1024); } while (0)
; #define PG8_WAIT_V(n) asm volatile("s_waitcnt vmcnt(" #n ")" ::: "memory")
; #define PG8_WAIT_L(n) asm volatile("s_waitcnt lgkmcnt(" #n ")" ::: "memory")
; __device__ __forceinline__ void gemm_phase(LAS unsigned char* lds, const Desc& g, int G, int cidx, int tid) {
;     ...
;         for (int t = 0; t < nt; t += 2) {
;             const bool last = (t == nt - 2);
;             const char* a1 = cA + (size_t)(t + 1) * kstep;
;             const char* a2 = last ? nA : cA + (size_t)(t + 2) * kstep; const char* b2 = last ? nB : cB + (size_t)(t + 2) * kstep;
;             const char* a3 = a2 + kstep; const char* b3 = b2 + kstep;
;             PG8_LDB(B0, 0, 0); PG8_LDB(B1, 0, 1); PG8_SCHED; PG8_LDA(At, 0, 0); PG8_STAGE(PG8_SA(1, 1), a1 + hstepA, voffA);
;             PG8_WAIT_V(8); PG8_WAIT_L(0); PG8_BAR; PG8_MMA(0, 0, At, B0); PG8_MMA(0, 1, At, B1); PG8_BAR; PG8_SCHED;
;             PG8_LDA(At, 0, 1); PG8_STAGE(PG8_SB(0, 0), b2, voffB); PG8_STAGE(PG8_SB(0, 1), b2 + hstepB, voffB); PG8_STAGE(PG8_SA(0, 0), a2, voffA);
;             PG8_WAIT_V(8); PG8_WAIT_L(0); PG8_BAR; PG8_MMA(1, 0, At, B0); PG8_MMA(1, 1, At, B1); PG8_BAR; PG8_SCHED;
;             PG8_LDB(B0, 1, 0); PG8_LDB(B1, 1, 1); PG8_SCHED; PG8_LDA(At, 1, 0); PG8_STAGE(PG8_SA(0, 1), a2 + hstepA, voffA);
;             PG8_WAIT_V(8); PG8_WAIT_L(0); PG8_BAR; PG8_MMA(0, 0, At, B0); PG8_MMA(0, 1, At, B1); PG8_BAR; PG8_SCHED;
;             PG8_LDA(At, 1, 1); PG8_STAGE(PG8_SB(1, 0), b3, voffB); PG8_STAGE(PG8_SB(1, 1), b3 + hstepB, voffB); PG8_STAGE(PG8_SA(1, 0), a3, voffA);
;             PG8_WAIT_V(8); PG8_WAIT_L(0); PG8_BAR; PG8_MMA(1, 0, At, B0); PG8_MMA(1, 1, At, B1); PG8_BAR; PG8_SCHED;
;         }
	s_setprio 1
	s_waitcnt lgkmcnt(0)
	v_mfma_f32_16x16x32_bf16 v[60:63], v[156:159], v[188:191], v[60:63]
	v_mfma_f32_16x16x32_bf16 v[56:59], v[164:167], v[188:191], v[56:59]
	v_mfma_f32_16x16x32_bf16 v[44:47], v[156:159], v[196:199], v[44:47]
	v_mfma_f32_16x16x32_bf16 v[40:43], v[164:167], v[196:199], v[40:43]
	v_mfma_f32_16x16x32_bf16 v[28:31], v[156:159], v[210:213], v[28:31]
	v_mfma_f32_16x16x32_bf16 v[24:27], v[164:167], v[210:213], v[24:27]
	v_mfma_f32_16x16x32_bf16 v[12:15], v[156:159], v[218:221], v[12:15]
	v_mfma_f32_16x16x32_bf16 v[8:11], v[164:167], v[218:221], v[8:11]
	v_mfma_f32_16x16x32_bf16 v[60:63], v[160:163], v[192:195], v[60:63]
	v_mfma_f32_16x16x32_bf16 v[56:59], v[168:171], v[192:195], v[56:59]
	v_mfma_f32_16x16x32_bf16 v[44:47], v[160:163], v[206:209], v[44:47]
	v_mfma_f32_16x16x32_bf16 v[40:43], v[168:171], v[206:209], v[40:43]
	v_mfma_f32_16x16x32_bf16 v[28:31], v[160:163], v[214:217], v[28:31]
	v_mfma_f32_16x16x32_bf16 v[24:27], v[168:171], v[214:217], v[24:27]
	v_mfma_f32_16x16x32_bf16 v[12:15], v[160:163], v[222:225], v[12:15]
	v_mfma_f32_16x16x32_bf16 v[8:11], v[168:171], v[222:225], v[8:11]
	s_setprio 0
	s_setprio 1
	v_mfma_f32_16x16x32_bf16 v[52:55], v[172:175], v[188:191], v[52:55]
	v_mfma_f32_16x16x32_bf16 v[48:51], v[180:183], v[188:191], v[48:51]
	v_mfma_f32_16x16x32_bf16 v[36:39], v[172:175], v[196:199], v[36:39]
	v_mfma_f32_16x16x32_bf16 v[32:35], v[180:183], v[196:199], v[32:35]
	v_mfma_f32_16x16x32_bf16 v[20:23], v[172:175], v[210:213], v[20:23]
	v_mfma_f32_16x16x32_bf16 v[16:19], v[180:183], v[210:213], v[16:19]
	v_mfma_f32_16x16x32_bf16 v[0:3], v[172:175], v[218:221], v[0:3]
	v_mfma_f32_16x16x32_bf16 v[4:7], v[180:183], v[218:221], v[4:7]
	v_mfma_f32_16x16x32_bf16 v[52:55], v[176:179], v[192:195], v[52:55]
	v_mfma_f32_16x16x32_bf16 v[48:51], v[184:187], v[192:195], v[48:51]
	v_mfma_f32_16x16x32_bf16 v[36:39], v[176:179], v[206:209], v[36:39]
	v_mfma_f32_16x16x32_bf16 v[32:35], v[184:187], v[206:209], v[32:35]
	v_mfma_f32_16x16x32_bf16 v[20:23], v[176:179], v[214:217], v[20:23]
	v_mfma_f32_16x16x32_bf16 v[16:19], v[184:187], v[214:217], v[16:19]
	v_mfma_f32_16x16x32_bf16 v[0:3], v[176:179], v[222:225], v[0:3]
	v_mfma_f32_16x16x32_bf16 v[4:7], v[184:187], v[222:225], v[4:7]
	s_setprio 0
	s_barrier
	s_add_i32 s42, 0, 0x18000
	v_add_u32_e32 v155, s42, v139
	s_add_i32 s43, 0, 0x1c000
	ds_read_b128 v[156:159], v155
	ds_read_b128 v[160:163], v155 offset:1024
	ds_read_b128 v[164:167], v155 offset:2048
	ds_read_b128 v[168:171], v155 offset:3072
	v_add_u32_e32 v155, s43, v139
	ds_read_b128 v[172:175], v155
	ds_read_b128 v[176:179], v155 offset:1024
	ds_read_b128 v[180:183], v155 offset:2048
	ds_read_b128 v[184:187], v155 offset:3072
	s_add_u32 s50, s58, 0x110000
	s_addc_u32 s51, s59, 0
	s_mov_b32 m0, s18
	v_lshl_add_u64 v[226:227], s[50:51], 0, v[132:133]
	ds_read_b128 v[188:191], v141 offset:32768
	ds_read_b128 v[192:195], v141 offset:33792
	ds_read_b128 v[196:199], v141 offset:34816
	ds_read_b128 v[206:209], v141 offset:35840
	ds_read_b128 v[210:213], v141 offset:36864
	ds_read_b128 v[214:217], v141 offset:37888
	ds_read_b128 v[218:221], v141 offset:38912
	ds_read_b128 v[222:225], v141 offset:39936
	global_load_lds_dwordx4 v[226:227], off
	v_lshl_add_u64 v[226:227], s[50:51], 0, v[130:131]
	s_mov_b32 m0, s24
	s_nop 0
	global_load_lds_dwordx4 v[226:227], off
	s_waitcnt vmcnt(8)
	s_barrier
	s_setprio 1
	s_waitcnt lgkmcnt(0)
	v_mfma_f32_16x16x32_bf16 v[124:127], v[156:159], v[188:191], v[124:127]
	v_mfma_f32_16x16x32_bf16 v[120:123], v[164:167], v[188:191], v[120:123]
	v_mfma_f32_16x16x32_bf16 v[108:111], v[156:159], v[196:199], v[108:111]
	v_mfma_f32_16x16x32_bf16 v[104:107], v[164:167], v[196:199], v[104:107]
	v_mfma_f32_16x16x32_bf16 v[92:95], v[156:159], v[210:213], v[92:95]
	v_mfma_f32_16x16x32_bf16 v[88:91], v[164:167], v[210:213], v[88:91]
	v_mfma_f32_16x16x32_bf16 v[76:79], v[156:159], v[218:221], v[76:79]
	v_mfma_f32_16x16x32_bf16 v[72:75], v[164:167], v[218:221], v[72:75]
	v_mfma_f32_16x16x32_bf16 v[124:127], v[160:163], v[192:195], v[124:127]
	v_mfma_f32_16x16x32_bf16 v[120:123], v[168:171], v[192:195], v[120:123]
	v_mfma_f32_16x16x32_bf16 v[108:111], v[160:163], v[206:209], v[108:111]
	v_mfma_f32_16x16x32_bf16 v[104:107], v[168:171], v[206:209], v[104:107]
	v_mfma_f32_16x16x32_bf16 v[92:95], v[160:163], v[214:217], v[92:95]
	v_mfma_f32_16x16x32_bf16 v[88:91], v[168:171], v[214:217], v[88:91]
	v_mfma_f32_16x16x32_bf16 v[76:79], v[160:163], v[222:225], v[76:79]
	v_mfma_f32_16x16x32_bf16 v[72:75], v[168:171], v[222:225], v[72:75]
	s_setprio 0
	s_setprio 1
	v_mfma_f32_16x16x32_bf16 v[116:119], v[172:175], v[188:191], v[116:119]
	v_mfma_f32_16x16x32_bf16 v[112:115], v[180:183], v[188:191], v[112:115]
	v_mfma_f32_16x16x32_bf16 v[100:103], v[172:175], v[196:199], v[100:103]
	v_mfma_f32_16x16x32_bf16 v[96:99], v[180:183], v[196:199], v[96:99]
	v_mfma_f32_16x16x32_bf16 v[84:87], v[172:175], v[210:213], v[84:87]
	v_mfma_f32_16x16x32_bf16 v[80:83], v[180:183], v[210:213], v[80:83]
	v_mfma_f32_16x16x32_bf16 v[68:71], v[172:175], v[218:221], v[68:71]
	v_mfma_f32_16x16x32_bf16 v[64:67], v[180:183], v[218:221], v[64:67]
	v_mfma_f32_16x16x32_bf16 v[116:119], v[176:179], v[192:195], v[116:119]
	v_mfma_f32_16x16x32_bf16 v[112:115], v[184:187], v[192:195], v[112:115]
	v_mfma_f32_16x16x32_bf16 v[100:103], v[176:179], v[206:209], v[100:103]
	v_mfma_f32_16x16x32_bf16 v[96:99], v[184:187], v[206:209], v[96:99]
	v_mfma_f32_16x16x32_bf16 v[84:87], v[176:179], v[214:217], v[84:87]
	v_mfma_f32_16x16x32_bf16 v[80:83], v[184:187], v[214:217], v[80:83]
	v_mfma_f32_16x16x32_bf16 v[68:71], v[176:179], v[222:225], v[68:71]
	v_mfma_f32_16x16x32_bf16 v[64:67], v[184:187], v[222:225], v[64:67]
	s_setprio 0
	s_barrier
; #define PG8_STAGE(bufoff, gbase, voff) do { _Pragma("unroll") for (int _i = 0; _i < 2; ++_i) \
;         __builtin_amdgcn_global_load_lds((const unsigned*)((const char*)(gbase) + (voff)[_i]), (LAS unsigned*)(lds + (bufoff) + ldsw + _i * 8192), 16, 0, 0); } while (0)
; #define PG8_LDA(dst, b, h) do { _Pragma("unroll") for (int m = 0; m < 4; ++m) _Pragma("unroll") for (int k = 0; k < 2; ++k) dst[m][k] = *(const LAS bf16x8*)(lds + PG8_SA(b, h) + aoff + m * 2048 + k * 1024); } while (0)
; #define PG8_LDB(dst, b, h) do { _Pragma("unroll") for (int n = 0; n < 2; ++n) _Pragma("unroll") for (int k = 0; k < 2; ++k) dst[n][k] = *(const LAS bf16x8*)(lds + PG8_SB(b, h) + boff + n * 2048 + k * 1024); } while (0)
; #define PG8_WAIT_V(n) asm volatile("s_waitcnt vmcnt(" #n ")" ::: "memory")
; #define PG8_WAIT_L(n) asm volatile("s_waitcnt lgkmcnt(" #n ")" ::: "memory")
; __device__ __forceinline__ void gemm_phase(LAS unsigned char* lds, const Desc& g, int G, int cidx, int tid) {
;     ...
;         for (int t = 0; t < nt; t += 2) {
;             const bool last = (t == nt - 2);
;             const char* a1 = cA + (size_t)(t + 1) * kstep;
;             const char* a2 = last ? nA : cA + (size_t)(t + 2) * kstep; const char* b2 = last ? nB : cB + (size_t)(t + 2) * kstep;
;             const char* a3 = a2 + kstep; const char* b3 = b2 + kstep;
;             PG8_LDB(B0, 0, 0); PG8_LDB(B1, 0, 1); PG8_SCHED; PG8_LDA(At, 0, 0); PG8_STAGE(PG8_SA(1, 1), a1 + hstepA, voffA);
;             PG8_WAIT_V(8); PG8_WAIT_L(0); PG8_BAR; PG8_MMA(0, 0, At, B0); PG8_MMA(0, 1, At, B1); PG8_BAR; PG8_SCHED;
;             PG8_LDA(At, 0, 1); PG8_STAGE(PG8_SB(0, 0), b2, voffB); PG8_STAGE(PG8_SB(0, 1), b2 + hstepB, voffB); PG8_STAGE(PG8_SA(0, 0), a2, voffA);
;             PG8_WAIT_V(8); PG8_WAIT_L(0); PG8_BAR; PG8_MMA(1, 0, At, B0); PG8_MMA(1, 1, At, B1); PG8_BAR; PG8_SCHED;
;             PG8_LDB(B0, 1, 0); PG8_LDB(B1, 1, 1); PG8_SCHED; PG8_LDA(At, 1, 0); PG8_STAGE(PG8_SA(0, 1), a2 + hstepA, voffA);
;             PG8_WAIT_V(8); PG8_WAIT_L(0); PG8_BAR; PG8_MMA(0, 0, At, B0); PG8_MMA(0, 1, At, B1); PG8_BAR; PG8_SCHED;
;             PG8_LDA(At, 1, 1); PG8_STAGE(PG8_SB(1, 0), b3, voffB); PG8_STAGE(PG8_SB(1, 1), b3 + hstepB, voffB); PG8_STAGE(PG8_SA(1, 0), a3, voffA);
;             PG8_WAIT_V(8); PG8_WAIT_L(0); PG8_BAR; PG8_MMA(1, 0, At, B0); PG8_MMA(1, 1, At, B1); PG8_BAR; PG8_SCHED;
;         }
	s_add_i32 s42, s42, s6
	v_lshl_add_u64 v[142:143], v[142:143], 0, s[22:23]
	s_mov_b32 m0, s42
	ds_read_b128 v[188:191], v141 offset:49152
	ds_read_b128 v[192:195], v141 offset:50176
	ds_read_b128 v[196:199], v141 offset:51200
	ds_read_b128 v[206:209], v141 offset:52224
	ds_read_b128 v[210:213], v141 offset:53248
	ds_read_b128 v[214:217], v141 offset:54272
	ds_read_b128 v[218:221], v141 offset:55296
	ds_read_b128 v[222:225], v141 offset:56320
	global_load_lds_dwordx4 v[142:143], off
	s_add_i32 m0, s42, 0x2000
	s_add_u32 s50, s56, 0x110080
	v_lshl_add_u64 v[142:143], v[146:147], 0, s[22:23]
	s_addc_u32 s51, s57, 0
	s_add_i32 s42, s43, s6
	global_load_lds_dwordx4 v[142:143], off
	v_lshl_add_u64 v[142:143], s[50:51], 0, v[144:145]
	s_mov_b32 m0, s42
	s_nop 0
	global_load_lds_dwordx4 v[142:143], off
	v_lshl_add_u64 v[142:143], s[50:51], 0, v[128:129]
	s_add_i32 m0, s42, 0x2000
	s_nop 0
	global_load_lds_dwordx4 v[142:143], off
	v_lshl_add_u64 v[142:143], v[148:149], 0, s[22:23]
	s_mov_b32 m0, s26
	s_nop 0
	global_load_lds_dwordx4 v[142:143], off
	v_lshl_add_u64 v[142:143], v[200:201], 0, s[22:23]
	s_mov_b32 m0, s28
	s_nop 0
	global_load_lds_dwordx4 v[142:143], off
	s_waitcnt vmcnt(8)
	s_barrier
	s_setprio 1
	s_waitcnt lgkmcnt(0)
	v_mfma_f32_16x16x32_bf16 v[60:63], v[156:159], v[188:191], v[60:63]
	v_mfma_f32_16x16x32_bf16 v[56:59], v[164:167], v[188:191], v[56:59]
	v_mfma_f32_16x16x32_bf16 v[44:47], v[156:159], v[196:199], v[44:47]
	v_mfma_f32_16x16x32_bf16 v[40:43], v[164:167], v[196:199], v[40:43]
	v_mfma_f32_16x16x32_bf16 v[28:31], v[156:159], v[210:213], v[28:31]
	v_mfma_f32_16x16x32_bf16 v[24:27], v[164:167], v[210:213], v[24:27]
	v_mfma_f32_16x16x32_bf16 v[12:15], v[156:159], v[218:221], v[12:15]
	v_mfma_f32_16x16x32_bf16 v[8:11], v[164:167], v[218:221], v[8:11]
	v_mfma_f32_16x16x32_bf16 v[60:63], v[160:163], v[192:195], v[60:63]
	v_mfma_f32_16x16x32_bf16 v[56:59], v[168:171], v[192:195], v[56:59]
	v_mfma_f32_16x16x32_bf16 v[44:47], v[160:163], v[206:209], v[44:47]
	v_mfma_f32_16x16x32_bf16 v[40:43], v[168:171], v[206:209], v[40:43]
	v_mfma_f32_16x16x32_bf16 v[28:31], v[160:163], v[214:217], v[28:31]
	v_mfma_f32_16x16x32_bf16 v[24:27], v[168:171], v[214:217], v[24:27]
	v_mfma_f32_16x16x32_bf16 v[12:15], v[160:163], v[222:225], v[12:15]
	v_mfma_f32_16x16x32_bf16 v[8:11], v[168:171], v[222:225], v[8:11]
	s_setprio 0
	s_setprio 1
	v_mfma_f32_16x16x32_bf16 v[52:55], v[172:175], v[188:191], v[52:55]
	v_mfma_f32_16x16x32_bf16 v[48:51], v[180:183], v[188:191], v[48:51]
	v_mfma_f32_16x16x32_bf16 v[36:39], v[172:175], v[196:199], v[36:39]
	v_mfma_f32_16x16x32_bf16 v[32:35], v[180:183], v[196:199], v[32:35]
	v_mfma_f32_16x16x32_bf16 v[20:23], v[172:175], v[210:213], v[20:23]
	v_mfma_f32_16x16x32_bf16 v[16:19], v[180:183], v[210:213], v[16:19]
	v_mfma_f32_16x16x32_bf16 v[0:3], v[172:175], v[218:221], v[0:3]
	v_mfma_f32_16x16x32_bf16 v[4:7], v[180:183], v[218:221], v[4:7]
	v_mfma_f32_16x16x32_bf16 v[52:55], v[176:179], v[192:195], v[52:55]
	v_mfma_f32_16x16x32_bf16 v[48:51], v[184:187], v[192:195], v[48:51]
	v_mfma_f32_16x16x32_bf16 v[36:39], v[176:179], v[206:209], v[36:39]
	v_mfma_f32_16x16x32_bf16 v[32:35], v[184:187], v[206:209], v[32:35]
	v_mfma_f32_16x16x32_bf16 v[20:23], v[176:179], v[214:217], v[20:23]
	v_mfma_f32_16x16x32_bf16 v[16:19], v[184:187], v[214:217], v[16:19]
	v_mfma_f32_16x16x32_bf16 v[0:3], v[176:179], v[222:225], v[0:3]
	v_mfma_f32_16x16x32_bf16 v[4:7], v[184:187], v[222:225], v[4:7]
	s_setprio 0
	s_barrier
	s_add_i32 s63, s63, 2
	s_add_u32 s61, s61, 0x100
	s_addc_u32 s62, s62, 0
	s_cmp_gt_u32 s63, 63
	s_mov_b64 s[50:51], s[52:53]
	s_cbranch_scc0 .LBB0_199
	s_and_b64 vcc, exec, s[36:37]
	s_cbranch_vccz .LBB0_202
	s_barrier

; #define PG8_STAGE(bufoff, gbase, voff) do { _Pragma("unroll") for (int _i = 0; _i < 2; ++_i) \
;         __builtin_amdgcn_global_load_lds((const unsigned*)((const char*)(gbase) + (voff)[_i]), (LAS unsigned*)(lds + (bufoff) + ldsw + _i * 8192), 16, 0, 0); } while (0)
; #define PG8_LDA(dst, b, h) do { _Pragma("unroll") for (int m = 0; m < 4; ++m) _Pragma("unroll") for (int k = 0; k < 2; ++k) dst[m][k] = *(const LAS bf16x8*)(lds + PG8_SA(b, h) + aoff + m * 2048 + k * 1024); } while (0)
; #define PG8_LDB(dst, b, h) do { _Pragma("unroll") for (int n = 0; n < 2; ++n) _Pragma("unroll") for (int k = 0; k < 2; ++k) dst[n][k] = *(const LAS bf16x8*)(lds + PG8_SB(b, h) + boff + n * 2048 + k * 1024); } while (0)
; #define PG8_WAIT_V(n) asm volatile("s_waitcnt vmcnt(" #n ")" ::: "memory")
; #define PG8_WAIT_L(n) asm volatile("s_waitcnt lgkmcnt(" #n ")" ::: "memory")
; __device__ __forceinline__ void gemm_phase(LAS unsigned char* lds, const Desc& g, int G, int cidx, int tid) {
;     ...
;         for (int t = 0; t < nt; t += 2) {
;             const bool last = (t == nt - 2);
;             const char* a1 = cA + (size_t)(t + 1) * kstep;
;             const char* a2 = last ? nA : cA + (size_t)(t + 2) * kstep; const char* b2 = last ? nB : cB + (size_t)(t + 2) * kstep;
;             const char* a3 = a2 + kstep; const char* b3 = b2 + kstep;
;             PG8_LDB(B0, 0, 0); PG8_LDB(B1, 0, 1); PG8_SCHED; PG8_LDA(At, 0, 0); PG8_STAGE(PG8_SA(1, 1), a1 + hstepA, voffA);
;             PG8_WAIT_V(8); PG8_WAIT_L(0); PG8_BAR; PG8_MMA(0, 0, At, B0); PG8_MMA(0, 1, At, B1); PG8_BAR; PG8_SCHED;
;             PG8_LDA(At, 0, 1); PG8_STAGE(PG8_SB(0, 0), b2, voffB); PG8_STAGE(PG8_SB(0, 1), b2 + hstepB, voffB); PG8_STAGE(PG8_SA(0, 0), a2, voffA);
;             PG8_WAIT_V(8); PG8_WAIT_L(0); PG8_BAR; PG8_MMA(1, 0, At, B0); PG8_MMA(1, 1, At, B1); PG8_BAR; PG8_SCHED;
;             PG8_LDB(B0, 1, 0); PG8_LDB(B1, 1, 1); PG8_SCHED; PG8_LDA(At, 1, 0); PG8_STAGE(PG8_SA(0, 1), a2 + hstepA, voffA);
;             PG8_WAIT_V(8); PG8_WAIT_L(0); PG8_BAR; PG8_MMA(0, 0, At, B0); PG8_MMA(0, 1, At, B1); PG8_BAR; PG8_SCHED;
;             PG8_LDA(At, 1, 1); PG8_STAGE(PG8_SB(1, 0), b3, voffB); PG8_STAGE(PG8_SB(1, 1), b3 + hstepB, voffB); PG8_STAGE(PG8_SA(1, 0), a3, voffA);
;             PG8_WAIT_V(8); PG8_WAIT_L(0); PG8_BAR; PG8_MMA(1, 0, At, B0); PG8_MMA(1, 1, At, B1); PG8_BAR; PG8_SCHED;
;         }
.LBB0_310:
	s_add_i32 s72, s40, 2
	s_add_u32 s4, s0, 0x80
	s_addc_u32 s5, s1, 0
	s_add_i32 s73, 0, 0x10000
	s_cmp_eq_u32 s60, s40
	s_cselect_b32 s41, s69, s5
	s_cselect_b32 s40, s68, s4
	v_add_u32_e32 v144, s73, v170
	s_cselect_b32 s43, s71, s75
	s_cselect_b32 s42, s70, s67
	s_add_i32 s4, 0, 0x14000
	ds_read_b128 v[128:131], v144
	ds_read_b128 v[132:135], v144 offset:1024
	ds_read_b128 v[146:149], v144 offset:2048
	ds_read_b128 v[158:161], v144 offset:3072
	v_add_u32_e32 v144, s4, v170
	ds_read_b128 v[162:165], v144
	ds_read_b128 v[166:169], v144 offset:1024
	ds_read_b128 v[174:177], v144 offset:2048
	ds_read_b128 v[178:181], v144 offset:3072
	v_lshl_add_u64 v[218:219], s[0:1], 0, v[156:157]
	s_add_i32 m0, s89, 0xc000
	ds_read_b128 v[182:185], v172
	ds_read_b128 v[186:189], v172 offset:1024
	ds_read_b128 v[190:193], v172 offset:2048
	ds_read_b128 v[194:197], v172 offset:3072
	ds_read_b128 v[198:201], v172 offset:4096
	ds_read_b128 v[206:209], v172 offset:5120
	ds_read_b128 v[210:213], v172 offset:6144
	ds_read_b128 v[214:217], v172 offset:7168
	global_load_lds_dwordx4 v[218:219], off
	v_lshl_add_u64 v[218:219], s[0:1], 0, v[154:155]
	s_add_i32 m0, s89, 0xe000
	s_nop 0
	global_load_lds_dwordx4 v[218:219], off
	s_waitcnt vmcnt(8)
	s_barrier
	s_setprio 1
	s_waitcnt lgkmcnt(0)
	v_mfma_f32_16x16x32_bf16 v[124:127], v[128:131], v[182:185], v[124:127]
	v_mfma_f32_16x16x32_bf16 v[120:123], v[146:149], v[182:185], v[120:123]
	v_mfma_f32_16x16x32_bf16 v[108:111], v[128:131], v[190:193], v[108:111]
	v_mfma_f32_16x16x32_bf16 v[104:107], v[146:149], v[190:193], v[104:107]
	v_mfma_f32_16x16x32_bf16 v[92:95], v[128:131], v[198:201], v[92:95]
	v_mfma_f32_16x16x32_bf16 v[88:91], v[146:149], v[198:201], v[88:91]
	v_mfma_f32_16x16x32_bf16 v[76:79], v[128:131], v[210:213], v[76:79]
	v_mfma_f32_16x16x32_bf16 v[72:75], v[146:149], v[210:213], v[72:75]
	v_mfma_f32_16x16x32_bf16 v[124:127], v[132:135], v[186:189], v[124:127]
	v_mfma_f32_16x16x32_bf16 v[120:123], v[158:161], v[186:189], v[120:123]
	v_mfma_f32_16x16x32_bf16 v[108:111], v[132:135], v[194:197], v[108:111]
	v_mfma_f32_16x16x32_bf16 v[104:107], v[158:161], v[194:197], v[104:107]
	v_mfma_f32_16x16x32_bf16 v[92:95], v[132:135], v[206:209], v[92:95]
	v_mfma_f32_16x16x32_bf16 v[88:91], v[158:161], v[206:209], v[88:91]
	v_mfma_f32_16x16x32_bf16 v[76:79], v[132:135], v[214:217], v[76:79]
	v_mfma_f32_16x16x32_bf16 v[72:75], v[158:161], v[214:217], v[72:75]
	s_setprio 0
	s_setprio 1
	v_mfma_f32_16x16x32_bf16 v[116:119], v[162:165], v[182:185], v[116:119]
	v_mfma_f32_16x16x32_bf16 v[112:115], v[174:177], v[182:185], v[112:115]
	v_mfma_f32_16x16x32_bf16 v[100:103], v[162:165], v[190:193], v[100:103]
	v_mfma_f32_16x16x32_bf16 v[96:99], v[174:177], v[190:193], v[96:99]
	v_mfma_f32_16x16x32_bf16 v[84:87], v[162:165], v[198:201], v[84:87]
	v_mfma_f32_16x16x32_bf16 v[80:83], v[174:177], v[198:201], v[80:83]
	v_mfma_f32_16x16x32_bf16 v[68:71], v[162:165], v[210:213], v[68:71]
	v_mfma_f32_16x16x32_bf16 v[64:67], v[174:177], v[210:213], v[64:67]
	v_mfma_f32_16x16x32_bf16 v[116:119], v[166:169], v[186:189], v[116:119]
	v_mfma_f32_16x16x32_bf16 v[112:115], v[178:181], v[186:189], v[112:115]
	v_mfma_f32_16x16x32_bf16 v[100:103], v[166:169], v[194:197], v[100:103]
	v_mfma_f32_16x16x32_bf16 v[96:99], v[178:181], v[194:197], v[96:99]
	v_mfma_f32_16x16x32_bf16 v[84:87], v[166:169], v[206:209], v[84:87]
	v_mfma_f32_16x16x32_bf16 v[80:83], v[178:181], v[206:209], v[80:83]
	v_mfma_f32_16x16x32_bf16 v[68:71], v[166:169], v[214:217], v[68:71]
	v_mfma_f32_16x16x32_bf16 v[64:67], v[178:181], v[214:217], v[64:67]
	s_setprio 0
	s_barrier
	s_add_i32 s5, s73, s88
	v_lshl_add_u64 v[218:219], s[42:43], 0, v[138:139]
	s_mov_b32 m0, s5
	ds_read_b128 v[182:185], v172 offset:16384
	ds_read_b128 v[186:189], v172 offset:17408
	ds_read_b128 v[190:193], v172 offset:18432
	ds_read_b128 v[194:197], v172 offset:19456
	ds_read_b128 v[198:201], v172 offset:20480
	ds_read_b128 v[206:209], v172 offset:21504
	ds_read_b128 v[210:213], v172 offset:22528
	ds_read_b128 v[214:217], v172 offset:23552
	global_load_lds_dwordx4 v[218:219], off
	s_add_i32 m0, s5, 0x2000
	v_lshl_add_u64 v[220:221], s[42:43], 0, v[142:143]
	s_add_u32 s42, s42, s99
	s_addc_u32 s43, s43, 0
	s_add_i32 s4, s4, s88
	global_load_lds_dwordx4 v[220:221], off
	v_lshl_add_u64 v[222:223], s[42:43], 0, v[138:139]
	s_mov_b32 m0, s4
	v_lshl_add_u64 v[224:225], s[42:43], 0, v[142:143]
	global_load_lds_dwordx4 v[222:223], off
	s_add_i32 m0, s4, 0x2000
	v_lshl_add_u64 v[226:227], s[40:41], 0, v[136:137]
	global_load_lds_dwordx4 v[224:225], off
	s_mov_b32 m0, s89
	v_lshl_add_u64 v[228:229], s[40:41], 0, v[140:141]
	global_load_lds_dwordx4 v[226:227], off
	s_mov_b32 m0, s90
	s_nop 0
	global_load_lds_dwordx4 v[228:229], off
	s_waitcnt vmcnt(8)
	s_barrier
; #define PG8_STAGE(bufoff, gbase, voff) do { _Pragma("unroll") for (int _i = 0; _i < 2; ++_i) \
;         __builtin_amdgcn_global_load_lds((const unsigned*)((const char*)(gbase) + (voff)[_i]), (LAS unsigned*)(lds + (bufoff) + ldsw + _i * 8192), 16, 0, 0); } while (0)
; #define PG8_LDA(dst, b, h) do { _Pragma("unroll") for (int m = 0; m < 4; ++m) _Pragma("unroll") for (int k = 0; k < 2; ++k) dst[m][k] = *(const LAS bf16x8*)(lds + PG8_SA(b, h) + aoff + m * 2048 + k * 1024); } while (0)
; #define PG8_LDB(dst, b, h) do { _Pragma("unroll") for (int n = 0; n < 2; ++n) _Pragma("unroll") for (int k = 0; k < 2; ++k) dst[n][k] = *(const LAS bf16x8*)(lds + PG8_SB(b, h) + boff + n * 2048 + k * 1024); } while (0)
; #define PG8_WAIT_V(n) asm volatile("s_waitcnt vmcnt(" #n ")" ::: "memory")
; #define PG8_WAIT_L(n) asm volatile("s_waitcnt lgkmcnt(" #n ")" ::: "memory")
; __device__ __forceinline__ void gemm_phase(LAS unsigned char* lds, const Desc& g, int G, int cidx, int tid) {
;     ...
;         for (int t = 0; t < nt; t += 2) {
;             const bool last = (t == nt - 2);
;             const char* a1 = cA + (size_t)(t + 1) * kstep;
;             const char* a2 = last ? nA : cA + (size_t)(t + 2) * kstep; const char* b2 = last ? nB : cB + (size_t)(t + 2) * kstep;
;             const char* a3 = a2 + kstep; const char* b3 = b2 + kstep;
;             PG8_LDB(B0, 0, 0); PG8_LDB(B1, 0, 1); PG8_SCHED; PG8_LDA(At, 0, 0); PG8_STAGE(PG8_SA(1, 1), a1 + hstepA, voffA);
;             PG8_WAIT_V(8); PG8_WAIT_L(0); PG8_BAR; PG8_MMA(0, 0, At, B0); PG8_MMA(0, 1, At, B1); PG8_BAR; PG8_SCHED;
;             PG8_LDA(At, 0, 1); PG8_STAGE(PG8_SB(0, 0), b2, voffB); PG8_STAGE(PG8_SB(0, 1), b2 + hstepB, voffB); PG8_STAGE(PG8_SA(0, 0), a2, voffA);
;             PG8_WAIT_V(8); PG8_WAIT_L(0); PG8_BAR; PG8_MMA(1, 0, At, B0); PG8_MMA(1, 1, At, B1); PG8_BAR; PG8_SCHED;
;             PG8_LDB(B0, 1, 0); PG8_LDB(B1, 1, 1); PG8_SCHED; PG8_LDA(At, 1, 0); PG8_STAGE(PG8_SA(0, 1), a2 + hstepA, voffA);
;             PG8_WAIT_V(8); PG8_WAIT_L(0); PG8_BAR; PG8_MMA(0, 0, At, B0); PG8_MMA(0, 1, At, B1); PG8_BAR; PG8_SCHED;
;             PG8_LDA(At, 1, 1); PG8_STAGE(PG8_SB(1, 0), b3, voffB); PG8_STAGE(PG8_SB(1, 1), b3 + hstepB, voffB); PG8_STAGE(PG8_SA(1, 0), a3, voffA);
;             PG8_WAIT_V(8); PG8_WAIT_L(0); PG8_BAR; PG8_MMA(1, 0, At, B0); PG8_MMA(1, 1, At, B1); PG8_BAR; PG8_SCHED;
;         }
	s_setprio 1
	s_waitcnt lgkmcnt(0)
	v_mfma_f32_16x16x32_bf16 v[60:63], v[128:131], v[182:185], v[60:63]
	v_mfma_f32_16x16x32_bf16 v[56:59], v[146:149], v[182:185], v[56:59]
	v_mfma_f32_16x16x32_bf16 v[44:47], v[128:131], v[190:193], v[44:47]
	v_mfma_f32_16x16x32_bf16 v[40:43], v[146:149], v[190:193], v[40:43]
	v_mfma_f32_16x16x32_bf16 v[28:31], v[128:131], v[198:201], v[28:31]
	v_mfma_f32_16x16x32_bf16 v[24:27], v[146:149], v[198:201], v[24:27]
	v_mfma_f32_16x16x32_bf16 v[12:15], v[128:131], v[210:213], v[12:15]
	v_mfma_f32_16x16x32_bf16 v[8:11], v[146:149], v[210:213], v[8:11]
	v_mfma_f32_16x16x32_bf16 v[60:63], v[132:135], v[186:189], v[60:63]
	v_mfma_f32_16x16x32_bf16 v[56:59], v[158:161], v[186:189], v[56:59]
	v_mfma_f32_16x16x32_bf16 v[44:47], v[132:135], v[194:197], v[44:47]
	v_mfma_f32_16x16x32_bf16 v[40:43], v[158:161], v[194:197], v[40:43]
	v_mfma_f32_16x16x32_bf16 v[28:31], v[132:135], v[206:209], v[28:31]
	v_mfma_f32_16x16x32_bf16 v[24:27], v[158:161], v[206:209], v[24:27]
	v_mfma_f32_16x16x32_bf16 v[12:15], v[132:135], v[214:217], v[12:15]
	v_mfma_f32_16x16x32_bf16 v[8:11], v[158:161], v[214:217], v[8:11]
	s_setprio 0
	s_setprio 1
	v_mfma_f32_16x16x32_bf16 v[52:55], v[162:165], v[182:185], v[52:55]
	v_mfma_f32_16x16x32_bf16 v[48:51], v[174:177], v[182:185], v[48:51]
	v_mfma_f32_16x16x32_bf16 v[36:39], v[162:165], v[190:193], v[36:39]
	v_mfma_f32_16x16x32_bf16 v[32:35], v[174:177], v[190:193], v[32:35]
	v_mfma_f32_16x16x32_bf16 v[20:23], v[162:165], v[198:201], v[20:23]
	v_mfma_f32_16x16x32_bf16 v[16:19], v[174:177], v[198:201], v[16:19]
	v_mfma_f32_16x16x32_bf16 v[0:3], v[162:165], v[210:213], v[0:3]
	v_mfma_f32_16x16x32_bf16 v[4:7], v[174:177], v[210:213], v[4:7]
	v_mfma_f32_16x16x32_bf16 v[52:55], v[166:169], v[186:189], v[52:55]
	v_mfma_f32_16x16x32_bf16 v[48:51], v[178:181], v[186:189], v[48:51]
	v_mfma_f32_16x16x32_bf16 v[36:39], v[166:169], v[194:197], v[36:39]
	v_mfma_f32_16x16x32_bf16 v[32:35], v[178:181], v[194:197], v[32:35]
	v_mfma_f32_16x16x32_bf16 v[20:23], v[166:169], v[206:209], v[20:23]
	v_mfma_f32_16x16x32_bf16 v[16:19], v[178:181], v[206:209], v[16:19]
	v_mfma_f32_16x16x32_bf16 v[0:3], v[166:169], v[214:217], v[0:3]
	v_mfma_f32_16x16x32_bf16 v[4:7], v[178:181], v[214:217], v[4:7]
	s_setprio 0
	s_barrier
	s_add_i32 s4, 0, 0x18000
	v_add_u32_e32 v144, s4, v170
	s_add_i32 s5, 0, 0x1c000
	ds_read_b128 v[128:131], v144
	ds_read_b128 v[132:135], v144 offset:1024
	ds_read_b128 v[146:149], v144 offset:2048
	ds_read_b128 v[158:161], v144 offset:3072
	v_add_u32_e32 v144, s5, v170
	ds_read_b128 v[162:165], v144
	ds_read_b128 v[166:169], v144 offset:1024
	ds_read_b128 v[174:177], v144 offset:2048
	ds_read_b128 v[178:181], v144 offset:3072
	s_add_u32 s40, s40, s2
	s_addc_u32 s41, s41, 0
	s_mov_b32 m0, s91
	v_lshl_add_u64 v[230:231], s[40:41], 0, v[136:137]
	ds_read_b128 v[182:185], v172 offset:32768
	ds_read_b128 v[186:189], v172 offset:33792
	ds_read_b128 v[190:193], v172 offset:34816
	ds_read_b128 v[194:197], v172 offset:35840
	ds_read_b128 v[198:201], v172 offset:36864
	ds_read_b128 v[206:209], v172 offset:37888
	ds_read_b128 v[210:213], v172 offset:38912
	ds_read_b128 v[214:217], v172 offset:39936
	global_load_lds_dwordx4 v[230:231], off
	v_lshl_add_u64 v[230:231], s[40:41], 0, v[140:141]
	s_mov_b32 m0, s92
	s_nop 0
	global_load_lds_dwordx4 v[230:231], off
	s_waitcnt vmcnt(8)
	s_barrier
	s_setprio 1
	s_waitcnt lgkmcnt(0)
	v_mfma_f32_16x16x32_bf16 v[124:127], v[128:131], v[182:185], v[124:127]
	v_mfma_f32_16x16x32_bf16 v[120:123], v[146:149], v[182:185], v[120:123]
	v_mfma_f32_16x16x32_bf16 v[108:111], v[128:131], v[190:193], v[108:111]
	v_mfma_f32_16x16x32_bf16 v[104:107], v[146:149], v[190:193], v[104:107]
	v_mfma_f32_16x16x32_bf16 v[92:95], v[128:131], v[198:201], v[92:95]
	v_mfma_f32_16x16x32_bf16 v[88:91], v[146:149], v[198:201], v[88:91]
	v_mfma_f32_16x16x32_bf16 v[76:79], v[128:131], v[210:213], v[76:79]
	v_mfma_f32_16x16x32_bf16 v[72:75], v[146:149], v[210:213], v[72:75]
	v_mfma_f32_16x16x32_bf16 v[124:127], v[132:135], v[186:189], v[124:127]
	v_mfma_f32_16x16x32_bf16 v[120:123], v[158:161], v[186:189], v[120:123]
	v_mfma_f32_16x16x32_bf16 v[108:111], v[132:135], v[194:197], v[108:111]
	v_mfma_f32_16x16x32_bf16 v[104:107], v[158:161], v[194:197], v[104:107]
	v_mfma_f32_16x16x32_bf16 v[92:95], v[132:135], v[206:209], v[92:95]
	v_mfma_f32_16x16x32_bf16 v[88:91], v[158:161], v[206:209], v[88:91]
	v_mfma_f32_16x16x32_bf16 v[76:79], v[132:135], v[214:217], v[76:79]
	v_mfma_f32_16x16x32_bf16 v[72:75], v[158:161], v[214:217], v[72:75]
	s_setprio 0
	s_setprio 1
	v_mfma_f32_16x16x32_bf16 v[116:119], v[162:165], v[182:185], v[116:119]
	v_mfma_f32_16x16x32_bf16 v[112:115], v[174:177], v[182:185], v[112:115]
	v_mfma_f32_16x16x32_bf16 v[100:103], v[162:165], v[190:193], v[100:103]
	v_mfma_f32_16x16x32_bf16 v[96:99], v[174:177], v[190:193], v[96:99]
	v_mfma_f32_16x16x32_bf16 v[84:87], v[162:165], v[198:201], v[84:87]
	v_mfma_f32_16x16x32_bf16 v[80:83], v[174:177], v[198:201], v[80:83]
	v_mfma_f32_16x16x32_bf16 v[68:71], v[162:165], v[210:213], v[68:71]
	v_mfma_f32_16x16x32_bf16 v[64:67], v[174:177], v[210:213], v[64:67]
	v_mfma_f32_16x16x32_bf16 v[116:119], v[166:169], v[186:189], v[116:119]
	v_mfma_f32_16x16x32_bf16 v[112:115], v[178:181], v[186:189], v[112:115]
	v_mfma_f32_16x16x32_bf16 v[100:103], v[166:169], v[194:197], v[100:103]
	v_mfma_f32_16x16x32_bf16 v[96:99], v[178:181], v[194:197], v[96:99]
	v_mfma_f32_16x16x32_bf16 v[84:87], v[166:169], v[206:209], v[84:87]
	v_mfma_f32_16x16x32_bf16 v[80:83], v[178:181], v[206:209], v[80:83]
	v_mfma_f32_16x16x32_bf16 v[68:71], v[166:169], v[214:217], v[68:71]
	v_mfma_f32_16x16x32_bf16 v[64:67], v[178:181], v[214:217], v[64:67]
	s_setprio 0
	s_barrier
; #define PG8_STAGE(bufoff, gbase, voff) do { _Pragma("unroll") for (int _i = 0; _i < 2; ++_i) \
;         __builtin_amdgcn_global_load_lds((const unsigned*)((const char*)(gbase) + (voff)[_i]), (LAS unsigned*)(lds + (bufoff) + ldsw + _i * 8192), 16, 0, 0); } while (0)
; #define PG8_LDA(dst, b, h) do { _Pragma("unroll") for (int m = 0; m < 4; ++m) _Pragma("unroll") for (int k = 0; k < 2; ++k) dst[m][k] = *(const LAS bf16x8*)(lds + PG8_SA(b, h) + aoff + m * 2048 + k * 1024); } while (0)
; #define PG8_LDB(dst, b, h) do { _Pragma("unroll") for (int n = 0; n < 2; ++n) _Pragma("unroll") for (int k = 0; k < 2; ++k) dst[n][k] = *(const LAS bf16x8*)(lds + PG8_SB(b, h) + boff + n * 2048 + k * 1024); } while (0)
; #define PG8_WAIT_V(n) asm volatile("s_waitcnt vmcnt(" #n ")" ::: "memory")
; #define PG8_WAIT_L(n) asm volatile("s_waitcnt lgkmcnt(" #n ")" ::: "memory")
; __device__ __forceinline__ void gemm_phase(LAS unsigned char* lds, const Desc& g, int G, int cidx, int tid) {
;     ...
;         for (int t = 0; t < nt; t += 2) {
;             const bool last = (t == nt - 2);
;             const char* a1 = cA + (size_t)(t + 1) * kstep;
;             const char* a2 = last ? nA : cA + (size_t)(t + 2) * kstep; const char* b2 = last ? nB : cB + (size_t)(t + 2) * kstep;
;             const char* a3 = a2 + kstep; const char* b3 = b2 + kstep;
;             PG8_LDB(B0, 0, 0); PG8_LDB(B1, 0, 1); PG8_SCHED; PG8_LDA(At, 0, 0); PG8_STAGE(PG8_SA(1, 1), a1 + hstepA, voffA);
;             PG8_WAIT_V(8); PG8_WAIT_L(0); PG8_BAR; PG8_MMA(0, 0, At, B0); PG8_MMA(0, 1, At, B1); PG8_BAR; PG8_SCHED;
;             PG8_LDA(At, 0, 1); PG8_STAGE(PG8_SB(0, 0), b2, voffB); PG8_STAGE(PG8_SB(0, 1), b2 + hstepB, voffB); PG8_STAGE(PG8_SA(0, 0), a2, voffA);
;             PG8_WAIT_V(8); PG8_WAIT_L(0); PG8_BAR; PG8_MMA(1, 0, At, B0); PG8_MMA(1, 1, At, B1); PG8_BAR; PG8_SCHED;
;             PG8_LDB(B0, 1, 0); PG8_LDB(B1, 1, 1); PG8_SCHED; PG8_LDA(At, 1, 0); PG8_STAGE(PG8_SA(0, 1), a2 + hstepA, voffA);
;             PG8_WAIT_V(8); PG8_WAIT_L(0); PG8_BAR; PG8_MMA(0, 0, At, B0); PG8_MMA(0, 1, At, B1); PG8_BAR; PG8_SCHED;
;             PG8_LDA(At, 1, 1); PG8_STAGE(PG8_SB(1, 0), b3, voffB); PG8_STAGE(PG8_SB(1, 1), b3 + hstepB, voffB); PG8_STAGE(PG8_SA(1, 0), a3, voffA);
;             PG8_WAIT_V(8); PG8_WAIT_L(0); PG8_BAR; PG8_MMA(1, 0, At, B0); PG8_MMA(1, 1, At, B1); PG8_BAR; PG8_SCHED;
;         }
	s_add_i32 s4, s4, s88
	v_lshl_add_u64 v[218:219], v[218:219], 0, s[22:23]
	s_mov_b32 m0, s4
	ds_read_b128 v[182:185], v172 offset:49152
	ds_read_b128 v[186:189], v172 offset:50176
	ds_read_b128 v[190:193], v172 offset:51200
	ds_read_b128 v[194:197], v172 offset:52224
	ds_read_b128 v[198:201], v172 offset:53248
	ds_read_b128 v[206:209], v172 offset:54272
	ds_read_b128 v[210:213], v172 offset:55296
	ds_read_b128 v[214:217], v172 offset:56320
	global_load_lds_dwordx4 v[218:219], off
	v_lshl_add_u64 v[218:219], v[220:221], 0, s[22:23]
	s_add_i32 m0, s4, 0x2000
	s_add_i32 s4, s5, s88
	global_load_lds_dwordx4 v[218:219], off
	v_lshl_add_u64 v[218:219], v[222:223], 0, s[22:23]
	s_mov_b32 m0, s4
	s_nop 0
	global_load_lds_dwordx4 v[218:219], off
	v_lshl_add_u64 v[218:219], v[224:225], 0, s[22:23]
	s_add_i32 m0, s4, 0x2000
	s_nop 0
	global_load_lds_dwordx4 v[218:219], off
	v_lshl_add_u64 v[218:219], v[226:227], 0, s[22:23]
	s_mov_b32 m0, s54
	s_nop 0
	global_load_lds_dwordx4 v[218:219], off
	v_lshl_add_u64 v[218:219], v[228:229], 0, s[22:23]
	s_mov_b32 m0, s55
	s_nop 0
	global_load_lds_dwordx4 v[218:219], off
	s_waitcnt vmcnt(8)
	s_barrier
	s_setprio 1
	s_waitcnt lgkmcnt(0)
	v_mfma_f32_16x16x32_bf16 v[60:63], v[128:131], v[182:185], v[60:63]
	v_mfma_f32_16x16x32_bf16 v[56:59], v[146:149], v[182:185], v[56:59]
	v_mfma_f32_16x16x32_bf16 v[44:47], v[128:131], v[190:193], v[44:47]
	v_mfma_f32_16x16x32_bf16 v[40:43], v[146:149], v[190:193], v[40:43]
	v_mfma_f32_16x16x32_bf16 v[28:31], v[128:131], v[198:201], v[28:31]
	v_mfma_f32_16x16x32_bf16 v[24:27], v[146:149], v[198:201], v[24:27]
	v_mfma_f32_16x16x32_bf16 v[12:15], v[128:131], v[210:213], v[12:15]
	v_mfma_f32_16x16x32_bf16 v[8:11], v[146:149], v[210:213], v[8:11]
	v_mfma_f32_16x16x32_bf16 v[60:63], v[132:135], v[186:189], v[60:63]
	v_mfma_f32_16x16x32_bf16 v[56:59], v[158:161], v[186:189], v[56:59]
	v_mfma_f32_16x16x32_bf16 v[44:47], v[132:135], v[194:197], v[44:47]
	v_mfma_f32_16x16x32_bf16 v[40:43], v[158:161], v[194:197], v[40:43]
	v_mfma_f32_16x16x32_bf16 v[28:31], v[132:135], v[206:209], v[28:31]
	v_mfma_f32_16x16x32_bf16 v[24:27], v[158:161], v[206:209], v[24:27]
	v_mfma_f32_16x16x32_bf16 v[12:15], v[132:135], v[214:217], v[12:15]
	v_mfma_f32_16x16x32_bf16 v[8:11], v[158:161], v[214:217], v[8:11]
	s_setprio 0
	s_setprio 1
	v_mfma_f32_16x16x32_bf16 v[52:55], v[162:165], v[182:185], v[52:55]
	v_mfma_f32_16x16x32_bf16 v[48:51], v[174:177], v[182:185], v[48:51]
	v_mfma_f32_16x16x32_bf16 v[36:39], v[162:165], v[190:193], v[36:39]
	v_mfma_f32_16x16x32_bf16 v[32:35], v[174:177], v[190:193], v[32:35]
	v_mfma_f32_16x16x32_bf16 v[20:23], v[162:165], v[198:201], v[20:23]
	v_mfma_f32_16x16x32_bf16 v[16:19], v[174:177], v[198:201], v[16:19]
	v_mfma_f32_16x16x32_bf16 v[0:3], v[162:165], v[210:213], v[0:3]
	v_mfma_f32_16x16x32_bf16 v[4:7], v[174:177], v[210:213], v[4:7]
	v_mfma_f32_16x16x32_bf16 v[52:55], v[166:169], v[186:189], v[52:55]
	v_mfma_f32_16x16x32_bf16 v[48:51], v[178:181], v[186:189], v[48:51]
	v_mfma_f32_16x16x32_bf16 v[36:39], v[166:169], v[194:197], v[36:39]
	v_mfma_f32_16x16x32_bf16 v[32:35], v[178:181], v[194:197], v[32:35]
	v_mfma_f32_16x16x32_bf16 v[20:23], v[166:169], v[206:209], v[20:23]
	v_mfma_f32_16x16x32_bf16 v[16:19], v[178:181], v[206:209], v[16:19]
	v_mfma_f32_16x16x32_bf16 v[0:3], v[166:169], v[214:217], v[0:3]
	v_mfma_f32_16x16x32_bf16 v[4:7], v[178:181], v[214:217], v[4:7]
	s_setprio 0
	s_barrier
	s_add_u32 s67, s67, 0x100
	s_addc_u32 s75, s75, 0
	s_add_u32 s0, s0, 0x100
	s_addc_u32 s1, s1, 0
	s_cmp_ge_u32 s72, s6
	s_mov_b32 s40, s72
	s_cbranch_scc0 .LBB0_310
	s_and_b64 vcc, exec, s[8:9]
	s_cbranch_vccz .LBB0_313
	s_barrier
